# expert_v fp4 conversion moved out of P9 into the idle P4 helper waves (one row per 8 scan rounds, loads kept in flight across a counted wait)
# speedup vs baseline: 1.0967x; 1.0125x over previous
; __global__ void __launch_bounds__(NT, 2) mk_fwd(Args args) {
;     ...
;         for (int task_ = bx; task_ < 256 * RMUL(4); task_ += G) {
;             const int tb_ = task_ & 255; const int task = ((tb_ >> 4) << 4) | ((tb_ & 7) << 1) | ((tb_ >> 3) & 1); const int bh = task >> 1, half = task & 1, b = bh >> 4, h = bh & 15;
;             const int stp = tid >> 4, q = tid & 15;
;             const size_t base = ((size_t)b * SEQ + stp) * 1024 + h * 64;
;             f32x4 ld_dec; u32x2 ld_kk, ld_bb, ld_kp, ld_rr; unsigned ld_vv;
.Lp4_helper:
	v_subrev_u32_e32 v54, 0x100, v168
	v_lshrrev_b32_e32 v55, 4, v54
	v_and_b32_e32 v56, 15, v54
	v_lshlrev_b32_e32 v57, 12, v55
	v_lshl_add_u32 v57, v56, 4, v57
	v_lshlrev_b32_e32 v58, 11, v55
	v_lshl_add_u32 v59, v56, 2, v58
	v_lshl_add_u32 v58, v56, 3, v58
	v_lshlrev_b32_e32 v60, 8, v55
	v_lshl_add_u32 v60, v56, 4, v60
	v_lshlrev_b32_e32 v61, 7, v55
	v_lshl_add_u32 v61, v56, 3, v61
	v_add_u32_e32 v61, 0x5000, v61
	v_mul_u32_u24_e32 v62, 0x90, v54
	v_add_u32_e32 v62, 0x14000, v62
	v_lshlrev_b32_e32 v63, 12, v55
	v_lshl_add_u32 v63, v56, 3, v63
	v_lshlrev_b32_e32 v50, 1, v60
	v_add_u32_e32 v50, 0x5800, v50
	v_lshlrev_b32_e32 v51, 1, v61
	v_add_u32_e32 v51, 0x5800, v51
	v_lshlrev_b32_e32 v52, 1, v62
	v_add_u32_e32 v52, 0xffff7000, v52
	v_xor_b32_e32 v174, 16, v128
	v_lshlrev_b32_e32 v174, 2, v174
	v_xor_b32_e32 v175, 32, v128
	v_lshlrev_b32_e32 v175, 2, v175
	v_xor_b32_e32 v176, 1, v128
	v_lshlrev_b32_e32 v176, 2, v176
	v_xor_b32_e32 v177, 2, v128
	v_lshlrev_b32_e32 v177, 2, v177
	v_xor_b32_e32 v178, 4, v128
	v_lshlrev_b32_e32 v178, 2, v178
	v_xor_b32_e32 v179, 8, v128
	v_lshlrev_b32_e32 v179, 2, v179
	v_mov_b32_e32 v180, 0x260
	v_mov_b32_e32 v227, 0
	v_lshlrev_b32_e32 v228, 4, v128
	v_lshlrev_b32_e32 v229, 7, v128
	v_cmp_eq_u32_e64 s[18:19], 0, v128
	s_mov_b32 s60, 0xf800000
	s_lshl_b32 s49, s2, 2
	s_add_i32 s49, s49, s85
	s_sub_i32 s49, s49, 4
	v_readlane_b32 s62, v249, 6
	v_readlane_b32 s63, v249, 7
	s_lshl_b32 s71, s49, 13
	s_add_u32 s62, s62, s71
	s_addc_u32 s63, s63, 0
	s_lshl_b32 s71, s49, 10
	s_add_u32 s64, s92, s71
	s_addc_u32 s65, s93, 0
	s_add_u32 s64, s64, 0x4a00000
	s_addc_u32 s65, s65, 0
	s_lshl_b32 s71, s49, 2
	s_add_u32 s58, s92, s71
	s_addc_u32 s59, s93, 0
	s_add_u32 s58, s58, 0x6a10000
	s_addc_u32 s59, s59, 0
	s_cmp_eq_u32 s84, 0x100
	s_cselect_b32 s67, 1, 0
	global_load_dwordx4 v[0:3], v57, s[38:39]
	global_load_dwordx2 v[4:5], v58, s[40:41]
	global_load_dwordx2 v[6:7], v58, s[42:43]
	global_load_dwordx2 v[8:9], v58, s[44:45]
	global_load_dwordx2 v[10:11], v58, s[46:47]
	global_load_dword v12, v59, s[52:53]
	v_add_u32_e32 v57, 0x10000, v57
	v_add_u32_e32 v58, 0x8000, v58
	v_add_u32_e32 v59, 0x8000, v59
	s_waitcnt vmcnt(0)
	ds_write_b128 v60, v[0:3]
	v_lshlrev_b32_e32 v16, 16, v4
	v_and_b32_e32 v17, 0xffff0000, v4
	v_lshlrev_b32_e32 v18, 16, v5
	v_and_b32_e32 v19, 0xffff0000, v5
	v_xor_b32_e32 v16, 0x80000000, v16
	v_xor_b32_e32 v17, 0x80000000, v17
	v_xor_b32_e32 v18, 0x80000000, v18
	v_xor_b32_e32 v19, 0x80000000, v19
	ds_write_b128 v60, v[16:19] offset:4096
	v_lshlrev_b32_e32 v20, 16, v6
	v_and_b32_e32 v21, 0xffff0000, v6
	v_lshlrev_b32_e32 v22, 16, v7
	v_and_b32_e32 v23, 0xffff0000, v7
	ds_write_b128 v60, v[20:23] offset:8192
	v_lshlrev_b32_e32 v24, 16, v8
	v_and_b32_e32 v25, 0xffff0000, v8
	v_lshlrev_b32_e32 v26, 16, v9
	v_and_b32_e32 v27, 0xffff0000, v9
	ds_write_b128 v60, v[24:27] offset:12288
	v_lshlrev_b32_e32 v28, 16, v10
	v_and_b32_e32 v29, 0xffff0000, v10
	v_lshlrev_b32_e32 v30, 16, v11
	v_and_b32_e32 v31, 0xffff0000, v11
	ds_write_b128 v60, v[28:31] offset:16384
	v_lshlrev_b32_e32 v14, 16, v12
	v_and_b32_e32 v15, 0xffff0000, v12
	ds_write_b64 v61, v[14:15]
	global_load_dwordx4 v[0:3], v57, s[38:39]
	global_load_dwordx2 v[4:5], v58, s[40:41]
	global_load_dwordx2 v[6:7], v58, s[42:43]
	global_load_dwordx2 v[8:9], v58, s[44:45]
	global_load_dwordx2 v[10:11], v58, s[46:47]
	global_load_dword v12, v59, s[52:53]
	v_add_u32_e32 v57, 0x10000, v57
	v_add_u32_e32 v58, 0x8000, v58
	v_add_u32_e32 v59, 0x8000, v59
	s_waitcnt lgkmcnt(0)
	s_barrier
	v_sub_u32_e32 v60, v50, v60
	v_sub_u32_e32 v61, v51, v61
	s_mov_b32 s10, 0
.Lp4_hround:
	s_and_b32 s66, s10, 7
	s_cmp_lt_u32 s10, 0x7f
	s_cbranch_scc0 .Lp4_hnostage
	s_cmp_eq_u32 s66, 1
	s_cbranch_scc0 .Lp4_hw0
	s_waitcnt vmcnt(8)
	s_branch .Lp4_hw1

.Lp4_hw1:
	ds_write_b128 v60, v[0:3]
	v_lshlrev_b32_e32 v16, 16, v4
	v_and_b32_e32 v17, 0xffff0000, v4
	v_lshlrev_b32_e32 v18, 16, v5
	v_and_b32_e32 v19, 0xffff0000, v5
	v_xor_b32_e32 v16, 0x80000000, v16
	v_xor_b32_e32 v17, 0x80000000, v17
	v_xor_b32_e32 v18, 0x80000000, v18
	v_xor_b32_e32 v19, 0x80000000, v19
	ds_write_b128 v60, v[16:19] offset:4096
	v_lshlrev_b32_e32 v20, 16, v6
	v_and_b32_e32 v21, 0xffff0000, v6
	v_lshlrev_b32_e32 v22, 16, v7
	v_and_b32_e32 v23, 0xffff0000, v7
	ds_write_b128 v60, v[20:23] offset:8192
	v_lshlrev_b32_e32 v24, 16, v8
	v_and_b32_e32 v25, 0xffff0000, v8
	v_lshlrev_b32_e32 v26, 16, v9
	v_and_b32_e32 v27, 0xffff0000, v9
	ds_write_b128 v60, v[24:27] offset:12288
	v_lshlrev_b32_e32 v28, 16, v10
	v_and_b32_e32 v29, 0xffff0000, v10
	v_lshlrev_b32_e32 v30, 16, v11
	v_and_b32_e32 v31, 0xffff0000, v11
	ds_write_b128 v60, v[28:31] offset:16384
	v_lshlrev_b32_e32 v14, 16, v12
	v_and_b32_e32 v15, 0xffff0000, v12
	ds_write_b64 v61, v[14:15]
	s_cmp_lt_u32 s10, 0x7e
	s_cbranch_scc0 .Lp4_hnostage
	global_load_dwordx4 v[0:3], v57, s[38:39]
	global_load_dwordx2 v[4:5], v58, s[40:41]
	global_load_dwordx2 v[6:7], v58, s[42:43]
	global_load_dwordx2 v[8:9], v58, s[44:45]
	global_load_dwordx2 v[10:11], v58, s[46:47]
	global_load_dword v12, v59, s[52:53]
	v_add_u32_e32 v57, 0x10000, v57
	v_add_u32_e32 v58, 0x8000, v58
	v_add_u32_e32 v59, 0x8000, v59

.Lp4_hnored:
	s_cmp_eq_u32 s67, 0
	s_cbranch_scc1 .Lp4_cv_done
	s_cmp_eq_u32 s66, 0
	s_cbranch_scc0 .Lp4_cv_notL
	global_load_dwordx4 v[92:95], v229, s[62:63]
	global_load_dwordx4 v[84:87], v229, s[62:63] offset:16
	global_load_dwordx4 v[76:79], v229, s[62:63] offset:32
	global_load_dwordx4 v[72:75], v229, s[62:63] offset:48
	global_load_dwordx4 v[100:103], v229, s[62:63] offset:64
	global_load_dwordx4 v[96:99], v229, s[62:63] offset:80
	global_load_dwordx4 v[88:91], v229, s[62:63] offset:96
	global_load_dwordx4 v[80:83], v229, s[62:63] offset:112
	s_add_u32 s62, s62, 0x800000
	s_addc_u32 s63, s63, 0
	s_branch .Lp4_cv_done
.Lp4_cv_notL:
	s_cmp_eq_u32 s66, 2
	s_cbranch_scc0 .Lp4_cv_done
	v_max_f32_e64 v181, |v95|, |v95|
	v_max_f32_e64 v199, |v94|, |v94|
	v_max_f32_e64 v201, |v87|, |v87|
	v_max_f32_e64 v203, |v86|, |v86|
	v_max_f32_e64 v205, |v79|, |v79|
	v_max_f32_e64 v206, |v78|, |v78|
	v_pk_mul_f32 v[182:183], v[78:79], v[78:79]
	v_pk_mul_f32 v[184:185], v[76:77], v[76:77]
	v_max_f32_e64 v208, |v75|, |v75|
	v_max_f32_e64 v209, |v74|, |v74|
	v_pk_mul_f32 v[186:187], v[98:99], v[98:99]
	v_pk_mul_f32 v[188:189], v[96:97], v[96:97]
	v_mov_b32_e32 v190, v93
	v_mov_b32_e32 v191, v85
	v_mov_b32_e32 v194, v95
	v_mov_b32_e32 v195, v87
	v_mul_f32_e32 v198, v73, v73
	v_mul_f32_e32 v200, v75, v75
	v_mul_f32_e32 v202, v89, v89
	v_mul_f32_e32 v204, v91, v91
	v_max_f32_e32 v181, v199, v181
	v_max_f32_e32 v226, v203, v201
	v_max_f32_e32 v205, v206, v205
	v_max_f32_e64 v210, |v103|, |v103|
	v_max_f32_e64 v211, |v102|, |v102|
	v_max_f32_e64 v216, |v99|, |v99|
	v_max_f32_e64 v217, |v98|, |v98|
	v_pk_mov_b32 v[206:207], v[184:185], v[182:183] op_sel:[1,0]
	v_mov_b32_e32 v185, v183
	v_max_f32_e32 v208, v209, v208
	v_pk_mov_b32 v[182:183], v[188:189], v[186:187] op_sel:[1,0]
	v_mov_b32_e32 v189, v187
	v_pk_mul_f32 v[186:187], v[190:191], v[190:191]
	v_pk_mul_f32 v[190:191], v[194:195], v[194:195]
	v_pk_fma_f32 v[194:195], v[72:73], v[72:73], v[198:199] op_sel_hi:[1,1,0]
	v_pk_fma_f32 v[198:199], v[74:75], v[74:75], v[200:201] op_sel_hi:[1,1,0]
	v_pk_fma_f32 v[200:201], v[88:89], v[88:89], v[202:203] op_sel_hi:[1,1,0]
	v_pk_fma_f32 v[202:203], v[90:91], v[90:91], v[204:205] op_sel_hi:[1,1,0]
	v_max3_f32 v181, |v92|, |v93|, v181
	v_max3_f32 v204, |v84|, |v85|, v226
	v_max_f32_e64 v218, |v91|, |v91|
	v_max_f32_e64 v219, |v90|, |v90|
	v_max_f32_e64 v220, |v83|, |v83|
	v_max_f32_e64 v221, |v82|, |v82|
	v_max_f32_e32 v209, v211, v210
	v_max_f32_e32 v210, v217, v216
	v_max3_f32 v205, |v76|, |v77|, v205
	v_pk_add_f32 v[184:185], v[206:207], v[184:185]
	v_max3_f32 v206, |v72|, |v73|, v208
	v_max3_f32 v181, v181, 0, v204
	v_max_f32_e32 v211, v219, v218
	v_max_f32_e32 v216, v221, v220
	v_max3_f32 v207, |v100|, |v101|, v209
	v_max3_f32 v208, |v96|, |v97|, v210
	v_max3_f32 v181, v181, v205, v206
	v_max3_f32 v209, |v88|, |v89|, v211
	v_max3_f32 v210, |v80|, |v81|, v216
	v_max3_f32 v181, v181, v207, v208
	v_mov_b32_e32 v192, v94
	v_mov_b32_e32 v193, v86
	v_max3_f32 v181, v181, v209, v210
	v_pk_add_f32 v[182:183], v[182:183], v[188:189]
	v_pk_fma_f32 v[188:189], v[192:193], v[192:193], v[190:191]
	ds_bpermute_b32 v192, v176, v181
	v_pk_add_f32 v[182:183], v[182:183], v[182:183] op_sel:[0,1] op_sel_hi:[1,0]
	v_mov_b32_e32 v196, v92
	v_mov_b32_e32 v197, v84
	v_pk_fma_f32 v[186:187], v[196:197], v[196:197], v[186:187]
	s_waitcnt lgkmcnt(0)
	v_max_f32_e32 v183, v192, v192
	v_max_f32_e32 v181, v181, v183
	ds_bpermute_b32 v192, v177, v181
	v_pk_add_f32 v[186:187], v[186:187], v[188:189]
	v_mul_f32_e32 v212, v100, v100
	v_mul_f32_e32 v213, v101, v101
	v_mul_f32_e32 v214, v102, v102
	v_mul_f32_e32 v215, v103, v103
	v_pk_add_f32 v[184:185], v[184:185], v[184:185] op_sel:[0,1] op_sel_hi:[1,0]
	v_pk_add_f32 v[186:187], v[186:187], v[186:187] op_sel:[0,1] op_sel_hi:[1,0]
	v_mov_b32_e32 v195, v214
	v_mov_b32_e32 v199, v215
	v_mov_b32_e32 v185, v213
	v_mov_b32_e32 v187, v212
	v_pk_add_f32 v[188:189], v[194:195], v[198:199]
	v_pk_add_f32 v[184:185], v[186:187], v[184:185]
	s_waitcnt lgkmcnt(0)
	v_max_f32_e32 v192, v192, v192
	v_pk_add_f32 v[184:185], v[184:185], v[188:189]
	v_mul_f32_e32 v222, v80, v80
	v_mul_f32_e32 v223, v81, v81
	v_mul_f32_e32 v224, v82, v82
	v_mul_f32_e32 v225, v83, v83
	v_max_f32_e32 v181, v181, v192
	v_pk_add_f32 v[184:185], v[184:185], v[184:185] op_sel:[0,1] op_sel_hi:[1,0]
	v_mov_b32_e32 v201, v224
	v_mov_b32_e32 v203, v225
	v_mov_b32_e32 v183, v223
	ds_bpermute_b32 v192, v178, v181
	v_mov_b32_e32 v185, v222
	v_pk_add_f32 v[190:191], v[200:201], v[202:203]
	v_pk_add_f32 v[182:183], v[184:185], v[182:183]
	s_waitcnt lgkmcnt(0)
	v_max_f32_e32 v186, v192, v192
	v_pk_add_f32 v[182:183], v[182:183], v[190:191]
	v_max_f32_e32 v181, v181, v186
	v_add_f32_e32 v182, v182, v183
	ds_bpermute_b32 v186, v179, v181
	s_waitcnt lgkmcnt(0)
	v_max_f32_e32 v184, v186, v186
	v_add_f32_dpp v182, v182, v182 quad_perm:[1,0,3,2] row_mask:0xf bank_mask:0xf bound_ctrl:1
	v_max_f32_e32 v181, v181, v184
	ds_bpermute_b32 v184, v174, v181
	v_add_f32_dpp v182, v182, v182 quad_perm:[2,3,0,1] row_mask:0xf bank_mask:0xf bound_ctrl:1
	s_waitcnt lgkmcnt(0)
	v_max_f32_e32 v184, v184, v184
	v_add_f32_dpp v182, v182, v182 row_half_mirror row_mask:0xf bank_mask:0xf bound_ctrl:1
	v_max_f32_e32 v181, v181, v184
	ds_bpermute_b32 v184, v175, v181
	v_add_f32_dpp v182, v182, v182 row_mirror row_mask:0xf bank_mask:0xf bound_ctrl:1
	ds_bpermute_b32 v183, v174, v182
	s_waitcnt lgkmcnt(1)
	v_max_f32_e32 v184, v184, v184
	v_max_f32_e32 v181, v181, v184
	s_waitcnt lgkmcnt(0)
	v_add_f32_e32 v182, v182, v183
	ds_bpermute_b32 v183, v175, v182
	v_mul_f32_e32 v181, 0x3de38e39, v181
	s_waitcnt lgkmcnt(0)
	v_add_f32_e32 v182, v182, v183
	v_mul_f32_e32 v182, 0x3a000000, v182
	v_mul_f32_e32 v183, 0x4f800000, v182
	v_cmp_gt_f32_e32 vcc, s60, v182
	s_nop 1
	v_cndmask_b32_e32 v182, v182, v183, vcc
	v_sqrt_f32_e32 v183, v182
	s_nop 0
	v_add_u32_e32 v184, -1, v183
	v_fma_f32 v185, -v184, v183, v182
	v_cmp_ge_f32_e64 s[14:15], 0, v185
	v_add_u32_e32 v185, 1, v183
	s_nop 0
	v_cndmask_b32_e64 v184, v183, v184, s[14:15]
	v_fma_f32 v183, -v185, v183, v182
	v_cmp_lt_f32_e64 s[14:15], 0, v183
	s_nop 1
	v_cndmask_b32_e64 v183, v184, v185, s[14:15]
	v_mul_f32_e32 v184, 0x37800000, v183
	v_cndmask_b32_e32 v183, v183, v184, vcc
	v_cmp_class_f32_e32 vcc, v182, v180
	s_nop 1
	v_cndmask_b32_e32 v182, v183, v182, vcc
	v_mul_f32_e32 v182, 0.5, v182
	v_max_f32_e32 v181, v182, v181
	v_cmp_lt_f32_e32 vcc, 0, v181
	s_nop 1
	v_cndmask_b32_e32 v181, 1.0, v181, vcc
	v_div_scale_f32 v182, s[14:15], v181, v181, 1.0
	v_rcp_f32_e32 v183, v182
	s_nop 0
	v_fma_f32 v184, -v182, v183, 1.0
	v_fmac_f32_e32 v183, v184, v183
	v_div_scale_f32 v184, vcc, 1.0, v181, 1.0
	v_mul_f32_e32 v185, v184, v183
	v_fma_f32 v186, -v182, v185, v184
	v_fmac_f32_e32 v185, v186, v183
	v_fma_f32 v182, -v182, v185, v184
	v_div_fmas_f32 v182, v182, v183, v185
	v_div_fixup_f32 v182, v182, v181, 1.0
	v_pk_mul_f32 v[92:93], v[182:183], v[92:93] op_sel_hi:[0,1]
	v_pk_mul_f32 v[184:185], v[182:183], v[84:85] op_sel_hi:[0,1]
	v_mov_b32_e32 v84, 0
	v_pk_mul_f32 v[76:77], v[182:183], v[76:77] op_sel_hi:[0,1]
	v_mov_b32_e32 v85, 0
	v_pk_mul_f32 v[94:95], v[182:183], v[94:95] op_sel_hi:[0,1]
	v_cvt_scalef32_pk_fp4_f32 v84, v92, v93, 1.0
	v_pk_mul_f32 v[78:79], v[182:183], v[78:79] op_sel_hi:[0,1]
	v_cvt_scalef32_pk_fp4_f32 v85, v76, v77, 1.0
	v_cvt_scalef32_pk_fp4_f32 v84, v94, v95, 1.0 op_sel:[0,0,1,0]
	v_pk_mul_f32 v[72:73], v[182:183], v[72:73] op_sel_hi:[0,1]
	v_cvt_scalef32_pk_fp4_f32 v85, v78, v79, 1.0 op_sel:[0,0,1,0]
	v_pk_mul_f32 v[86:87], v[182:183], v[86:87] op_sel_hi:[0,1]
	v_cvt_scalef32_pk_fp4_f32 v84, v184, v185, 1.0 op_sel:[0,0,0,1]
	v_pk_mul_f32 v[74:75], v[182:183], v[74:75] op_sel_hi:[0,1]
	v_cvt_scalef32_pk_fp4_f32 v85, v72, v73, 1.0 op_sel:[0,0,0,1]
	v_cvt_scalef32_pk_fp4_f32 v84, v86, v87, 1.0 op_sel:[0,0,1,1]
	v_cvt_scalef32_pk_fp4_f32 v85, v74, v75, 1.0 op_sel:[0,0,1,1]
	v_pk_mul_f32 v[74:75], v[182:183], v[100:101] op_sel_hi:[0,1]
	v_mov_b32_e32 v86, 0
	v_pk_mul_f32 v[72:73], v[182:183], v[102:103] op_sel_hi:[0,1]
	v_cvt_scalef32_pk_fp4_f32 v86, v74, v75, 1.0
	v_pk_mul_f32 v[74:75], v[182:183], v[88:89] op_sel_hi:[0,1]
	v_mov_b32_e32 v87, 0
	v_pk_mul_f32 v[78:79], v[182:183], v[96:97] op_sel_hi:[0,1]
	v_cvt_scalef32_pk_fp4_f32 v86, v72, v73, 1.0 op_sel:[0,0,1,0]
	v_pk_mul_f32 v[72:73], v[182:183], v[90:91] op_sel_hi:[0,1]
	v_cvt_scalef32_pk_fp4_f32 v87, v74, v75, 1.0
	v_pk_mul_f32 v[76:77], v[182:183], v[98:99] op_sel_hi:[0,1]
	v_cvt_scalef32_pk_fp4_f32 v86, v78, v79, 1.0 op_sel:[0,0,0,1]
	v_pk_mul_f32 v[78:79], v[182:183], v[80:81] op_sel_hi:[0,1]
	v_cvt_scalef32_pk_fp4_f32 v87, v72, v73, 1.0 op_sel:[0,0,1,0]
	v_cvt_scalef32_pk_fp4_f32 v86, v76, v77, 1.0 op_sel:[0,0,1,1]
	v_pk_mul_f32 v[76:77], v[182:183], v[82:83] op_sel_hi:[0,1]
	v_cvt_scalef32_pk_fp4_f32 v87, v78, v79, 1.0 op_sel:[0,0,0,1]
	s_nop 0
	v_cvt_scalef32_pk_fp4_f32 v87, v76, v77, 1.0 op_sel:[0,0,1,1]
	global_store_dwordx4 v228, v[84:87], s[64:65]
	s_and_saveexec_b64 s[14:15], s[18:19]
	s_cbranch_execz .Lp4_cv_nost
	global_store_dword v227, v181, s[58:59]
.Lp4_cv_nost:
	s_or_b64 exec, exec, s[14:15]
	s_add_u32 s64, s64, 0x100000
	s_addc_u32 s65, s65, 0
	s_add_u32 s58, s58, 0x1000
	s_addc_u32 s59, s59, 0

; __global__ void __launch_bounds__(NT, 2) mk_fwd(Args args) {
;     ...
;         CONVERT_EXPERT_FP4_ROWS(args.in[27], PV8, SCL + 16384, gw, NGW);
;     }
.LBB0_824:
	v_readlane_b32 s86, v249, 27
	v_readlane_b32 s87, v249, 28
	v_readlane_b32 s74, v249, 38
	v_readlane_b32 s78, v249, 35
	v_readlane_b32 s82, v249, 29
	v_readlane_b32 s20, v249, 33
	s_andn2_b64 vcc, exec, s[86:87]
	v_readlane_b32 s70, v249, 40
	v_readlane_b32 s75, v249, 39
	v_readlane_b32 s77, v249, 37
	v_readlane_b32 s84, v249, 24
	v_readlane_b32 s79, v249, 36
	v_readlane_b32 s83, v249, 30
	v_readlane_b32 s21, v249, 34
	v_readlane_b32 s71, v249, 41
	s_cbranch_vccnz .LBB0_829
	s_cmp_eq_u32 s84, 0x100
	s_cbranch_scc1 .LBB0_829
	s_waitcnt vmcnt(0)
	v_mbcnt_hi_u32_b32 v0, -1, v169
	v_and_b32_e32 v1, 64, v0
	v_add_u32_e32 v1, 64, v1
	v_xor_b32_e32 v2, 16, v0
	v_cmp_lt_i32_e32 vcc, v2, v1
	s_ashr_i32 s71, s70, 31
	s_lshl_b64 s[0:1], s[70:71], 2
	v_cndmask_b32_e32 v2, v0, v2, vcc
	v_lshlrev_b32_e32 v36, 2, v2
	v_xor_b32_e32 v2, 32, v0
	v_cmp_lt_i32_e32 vcc, v2, v1
	s_add_u32 s0, s92, s0
	s_addc_u32 s1, s93, s1
	v_cndmask_b32_e32 v2, v0, v2, vcc
	v_lshlrev_b32_e32 v37, 2, v2
	v_xor_b32_e32 v2, 1, v0
	v_cmp_lt_i32_e32 vcc, v2, v1
	s_add_u32 s4, s0, 0x6a10000
	s_addc_u32 s5, s1, 0
	v_cndmask_b32_e32 v2, v0, v2, vcc
	v_lshlrev_b32_e32 v38, 2, v2
	v_xor_b32_e32 v2, 2, v0
	v_cmp_lt_i32_e32 vcc, v2, v1
	s_ashr_i32 s73, s72, 31
	s_lshl_b64 s[6:7], s[72:73], 2
	v_cndmask_b32_e32 v2, v0, v2, vcc
	v_lshlrev_b32_e32 v39, 2, v2
	v_xor_b32_e32 v2, 4, v0
	v_cmp_lt_i32_e32 vcc, v2, v1
	s_lshl_b64 s[0:1], s[70:71], 10
	s_add_u32 s0, s92, s0
	v_cndmask_b32_e32 v2, v0, v2, vcc
	v_lshlrev_b32_e32 v40, 2, v2
	v_xor_b32_e32 v2, 8, v0
	v_cmp_lt_i32_e32 vcc, v2, v1
	v_mov_b32_e32 v131, 0
	s_addc_u32 s1, s93, s1
	v_cndmask_b32_e32 v0, v0, v2, vcc
	v_readlane_b32 s12, v249, 0
	v_lshlrev_b32_e32 v41, 2, v0
	v_lshl_add_u64 v[0:1], s[0:1], 0, v[130:131]
	s_mov_b64 s[0:1], 0x4a00000
	v_readlane_b32 s18, v249, 6
	v_readlane_b32 s19, v249, 7
	v_lshl_add_u64 v[32:33], v[0:1], 0, s[0:1]
	s_lshl_b64 s[8:9], s[72:73], 10
	s_lshl_b64 s[0:1], s[70:71], 13
	s_mov_b64 s[10:11], s[18:19]
	s_add_u32 s0, s10, s0
	v_lshlrev_b32_e32 v0, 7, v128
	v_mov_b32_e32 v1, v131
	s_addc_u32 s1, s11, s1
	v_readlane_b32 s13, v249, 1
	v_lshl_add_u64 v[0:1], s[0:1], 0, v[0:1]
	s_mov_b64 s[0:1], 0x70
	v_cmp_eq_u32_e64 s[2:3], 0, v128
	v_lshl_add_u64 v[34:35], v[0:1], 0, s[0:1]
	s_lshl_b64 s[10:11], s[72:73], 13
	s_mov_b32 s12, 0xf800000
	v_mov_b32_e32 v42, 0x260
	s_mov_b32 s13, s70
	v_readlane_b32 s14, v249, 2
	v_readlane_b32 s15, v249, 3
	v_readlane_b32 s16, v249, 4
	v_readlane_b32 s17, v249, 5
	s_branch .LBB0_827
